# attention loop software-pipelined: QK of tile u overlaps softmax/PV of tile u-1 (second score register set, V staged one tile later)
# speedup vs baseline: 1.0064x; 1.0064x over previous
; #define LAS __attribute__((address_space(3)))
; __device__ __forceinline__ void attn_tile(int t, int buf, LAS unsigned char* lds, const bf16x8 (&qr)[4], float cq2, int qlo, int qpos, int q32, int hi,
;                                           float& mrun, float& lrun, f32x16& o0, f32x16& o1) {
;     const LAS float* c2s = (const LAS float*)(lds + AT_C2);
;     const LAS unsigned char* Kt = lds + AT_K + buf * AT_KB; const LAS unsigned char* Vt = lds + AT_VT + buf * AT_VB;
;     f32x16 s0, s1;
; #pragma unroll
;     for (int j = 0; j < 4; ++j) {
;         const f32x4 c0 = *(const LAS f32x4*)(c2s + 64 * t + 8 * j + 4 * hi), c1 = *(const LAS f32x4*)(c2s + 64 * t + 32 + 8 * j + 4 * hi);
; #pragma unroll
;         for (int e = 0; e < 4; ++e) { s0[4 * j + e] = c0[e]; s1[4 * j + e] = c1[e]; }
;     }
; #pragma unroll
;     for (int d0 = 0; d0 < 4; ++d0) {
;         const bf16x8 k0 = *(const LAS bf16x8*)(Kt + q32 * 144 + d0 * 32 + hi * 16);
;         const bf16x8 k1 = *(const LAS bf16x8*)(Kt + (32 + q32) * 144 + d0 * 32 + hi * 16);
;         s0 = __builtin_amdgcn_mfma_f32_32x32x16_bf16(k0, qr[d0], s0, 0, 0, 0);
;         s1 = __builtin_amdgcn_mfma_f32_32x32x16_bf16(k1, qr[d0], s1, 0, 0, 0);
;     }
; __device__ __forceinline__ void attn_unit(const AttnJob& J, LAS unsigned char* lds) {
;     ...
;     for (int t = 0; t < J.NT; t += 2) {
;         attn_stage(lds, 0, kA, vA);
;         __syncthreads();
;         if (t + 2 < J.NT) attn_load(J, t + 2, kA, vA);
;         if (active && 64 * t <= qlo + 31) attn_tile(t, 0, lds, qr, cq2, qlo, qpos, q32, hi, mrun, lrun, o0, o1);
;         if (t + 1 < J.NT) {
;             attn_stage(lds, 1, kB, vB);
;             __syncthreads();
;             if (t + 3 < J.NT) attn_load(J, t + 3, kB, vB);
;             if (active && 64 * (t + 1) <= qlo + 31) attn_tile(t + 1, 1, lds, qr, cq2, qlo, qpos, q32, hi, mrun, lrun, o0, o1);
;         }
;     }
.LBB0_645:
	s_mov_b32 s22, 0
	s_mov_b32 s26, 0
	s_mov_b32 s27, 0
.Lslot_E:
	s_waitcnt vmcnt(2)
	ds_write_b128 v156, v[82:85] offset:8448
	s_cmp_eq_u32 s22, 0
	s_cbranch_scc1 .LnoV_E
	ds_write_b16 v157, v94 offset:35584
	ds_write_b16_d16_hi v157, v94 offset:35720
	ds_write_b16 v157, v95 offset:35856
	ds_write_b16_d16_hi v157, v95 offset:35992
	ds_write_b16 v157, v96 offset:36128
	ds_write_b16_d16_hi v157, v96 offset:36264
	ds_write_b16 v157, v97 offset:36400
	ds_write_b16_d16_hi v157, v97 offset:36536
.LnoV_E:
	s_waitcnt lgkmcnt(0)
	s_barrier
	s_add_i32 s6, s22, 2
	s_lshl_b32 s6, s6, 18
	s_add_u32 s98, s8, s6
	s_addc_u32 s99, s9, 0
	global_load_dwordx4 v[82:85], v158, s[98:99] offset:1024
	s_sub_u32 s100, s98, 0x40000
	s_subb_u32 s101, s99, 0
	global_load_dwordx4 v[94:97], v158, s[100:101] offset:2048
	s_lshl_b32 s6, s22, 6
	s_cmp_le_i32 s6, s23
	s_cbranch_scc0 .Lnoproc_E
	ds_read_b128 v[124:127], v112 offset:8448
	ds_read_b128 v[34:37], v111
	ds_read_b128 v[38:41], v111 offset:32
	ds_read_b128 v[42:45], v111 offset:64
	ds_read_b128 v[46:49], v111 offset:96
	ds_read_b128 v[128:131], v112 offset:13056
	ds_read_b128 v[50:53], v111 offset:128
	ds_read_b128 v[54:57], v111 offset:160
	ds_read_b128 v[58:61], v111 offset:192
	ds_read_b128 v[62:65], v111 offset:224
	ds_read_b128 v[132:135], v112 offset:8480
	ds_read_b128 v[136:139], v112 offset:13088
	ds_read_b128 v[140:143], v112 offset:8512
	ds_read_b128 v[144:147], v112 offset:13120
	s_cmp_eq_u32 s27, 0
	s_cbranch_scc1 .Lqkonly_E
	v_pk_add_f32 v[206:207], v[206:207], v[114:115] op_sel_hi:[1,0] neg_lo:[0,1] neg_hi:[0,1]
	v_pk_add_f32 v[208:209], v[208:209], v[114:115] op_sel_hi:[1,0] neg_lo:[0,1] neg_hi:[0,1]
	v_pk_add_f32 v[210:211], v[210:211], v[114:115] op_sel_hi:[1,0] neg_lo:[0,1] neg_hi:[0,1]
	v_pk_add_f32 v[212:213], v[212:213], v[114:115] op_sel_hi:[1,0] neg_lo:[0,1] neg_hi:[0,1]
	v_exp_f32_e32 v206, v206
	v_exp_f32_e32 v207, v207
	v_exp_f32_e32 v208, v208
	v_exp_f32_e32 v209, v209
	v_exp_f32_e32 v210, v210
	v_exp_f32_e32 v211, v211
	v_exp_f32_e32 v212, v212
	v_exp_f32_e32 v213, v213
	v_cvt_pk_bf16_f32 v118, v206, v207
	v_cvt_pk_bf16_f32 v119, v208, v209
	v_cvt_pk_bf16_f32 v120, v210, v211
	v_cvt_pk_bf16_f32 v121, v212, v213
	v_pk_add_f32 v[116:117], v[206:207], v[208:209]
	v_pk_add_f32 v[210:211], v[210:211], v[212:213]
	v_pk_add_f32 v[116:117], v[116:117], v[210:211]
	s_waitcnt lgkmcnt(9)
	v_mfma_f32_32x32x16_bf16 v[34:49], v[124:127], v[78:81], v[34:49]
	ds_read_b128 v[148:151], v112 offset:8544
	ds_read_b128 v[152:155], v112 offset:13152
	s_waitcnt lgkmcnt(6)
	v_mfma_f32_32x32x16_bf16 v[50:65], v[128:131], v[78:81], v[50:65]
	s_waitcnt lgkmcnt(5)
	v_mfma_f32_32x32x16_bf16 v[34:49], v[132:135], v[74:77], v[34:49]
	s_waitcnt lgkmcnt(4)
	v_mfma_f32_32x32x16_bf16 v[50:65], v[136:139], v[74:77], v[50:65]
	s_waitcnt lgkmcnt(3)
	v_mfma_f32_32x32x16_bf16 v[34:49], v[140:143], v[70:73], v[34:49]
	s_waitcnt lgkmcnt(2)
	v_mfma_f32_32x32x16_bf16 v[50:65], v[144:147], v[70:73], v[50:65]
	s_waitcnt lgkmcnt(1)
	v_mfma_f32_32x32x16_bf16 v[34:49], v[148:151], v[66:69], v[34:49]
	s_waitcnt lgkmcnt(0)
	v_mfma_f32_32x32x16_bf16 v[50:65], v[152:155], v[66:69], v[50:65]
	v_add_u32_e32 v122, 0x8800, v113
	v_add_u32_e32 v123, 0x9800, v113
	ds_read2_b64 v[166:169], v122 offset0:96 offset1:98
	ds_read2_b64 v[170:173], v123 offset0:128 offset1:130
	ds_read2_b64 v[174:177], v122 offset0:100 offset1:102
	ds_read2_b64 v[178:181], v123 offset0:132 offset1:134
	ds_read2_b64 v[182:185], v122 offset0:104 offset1:106
	ds_read2_b64 v[186:189], v123 offset0:136 offset1:138
	ds_read2_b64 v[190:193], v122 offset0:108 offset1:110
	ds_read2_b64 v[194:197], v123 offset0:140 offset1:142
	v_pk_add_f32 v[214:215], v[214:215], v[114:115] op_sel_hi:[1,0] neg_lo:[0,1] neg_hi:[0,1]
	v_pk_add_f32 v[216:217], v[216:217], v[114:115] op_sel_hi:[1,0] neg_lo:[0,1] neg_hi:[0,1]
	v_pk_add_f32 v[218:219], v[218:219], v[114:115] op_sel_hi:[1,0] neg_lo:[0,1] neg_hi:[0,1]
	v_pk_add_f32 v[220:221], v[220:221], v[114:115] op_sel_hi:[1,0] neg_lo:[0,1] neg_hi:[0,1]
	v_exp_f32_e32 v214, v214
	v_exp_f32_e32 v215, v215
	v_exp_f32_e32 v216, v216
	v_exp_f32_e32 v217, v217
	v_exp_f32_e32 v218, v218
	v_exp_f32_e32 v219, v219
	v_exp_f32_e32 v220, v220
	v_exp_f32_e32 v221, v221
	s_waitcnt lgkmcnt(0)
; #define LAS __attribute__((address_space(3)))
; __device__ __forceinline__ float fexp2(float x) { return __builtin_amdgcn_exp2f(x); }
; __device__ __forceinline__ void attn_tile(int t, int buf, LAS unsigned char* lds, const bf16x8 (&qr)[4], float cq2, int qlo, int qpos, int q32, int hi,
;                                           float& mrun, float& lrun, f32x16& o0, f32x16& o1) {
;     ...
;     if (64 * t + 63 > qlo) {
; #pragma unroll
;         for (int r = 0; r < 16; ++r) { const int kv = 64 * t + crow(r, hi); if (kv > qpos) s0[r] = -INFINITY; if (kv + 32 > qpos) s1[r] = -INFINITY; }
;     }
;     ...
;     f32x2 ls2 = (f32x2){0.f, 0.f};
; #pragma unroll
;     for (int r = 0; r < 16; r += 2) {
;         const f32x2 d0 = (f32x2){s0[r], s0[r + 1]} - mnew, d1 = (f32x2){s1[r], s1[r + 1]} - mnew;
;         f32x2 e0, e1; e0.x = fexp2(d0.x); e0.y = fexp2(d0.y); e1.x = fexp2(d1.x); e1.y = fexp2(d1.y);
;         s0[r] = e0.x; s0[r + 1] = e0.y; s1[r] = e1.x; s1[r + 1] = e1.y;
;         ls2 += e0 + e1;
;     }
;     lrun += ls2.x + ls2.y;
; #pragma unroll
;     for (int p = 0; p < 2; ++p)
; #pragma unroll
;         for (int sx = 0; sx < 2; ++sx) {
;             u32x4 pw;
;             if (p == 0) pw = (u32x4){pk_bf16(s0[8 * sx + 0], s0[8 * sx + 1]), pk_bf16(s0[8 * sx + 2], s0[8 * sx + 3]), pk_bf16(s0[8 * sx + 4], s0[8 * sx + 5]), pk_bf16(s0[8 * sx + 6], s0[8 * sx + 7])};
;             else        pw = (u32x4){pk_bf16(s1[8 * sx + 0], s1[8 * sx + 1]), pk_bf16(s1[8 * sx + 2], s1[8 * sx + 3]), pk_bf16(s1[8 * sx + 4], s1[8 * sx + 5]), pk_bf16(s1[8 * sx + 6], s1[8 * sx + 7])};
;             const bf16x8 pf = __builtin_bit_cast(bf16x8, pw);
;             const int ko = (32 * p + 16 * sx + 4 * hi) * 2;
;             const u32x2 a0 = *(const LAS u32x2*)(Vt + q32 * 136 + ko), a1 = *(const LAS u32x2*)(Vt + q32 * 136 + ko + 16);
;             const u32x2 b0 = *(const LAS u32x2*)(Vt + (32 + q32) * 136 + ko), b1 = *(const LAS u32x2*)(Vt + (32 + q32) * 136 + ko + 16);
;             const bf16x8 vf0 = __builtin_bit_cast(bf16x8, (u32x4){a0.x, a0.y, a1.x, a1.y});
;             const bf16x8 vf1 = __builtin_bit_cast(bf16x8, (u32x4){b0.x, b0.y, b1.x, b1.y});
;             o0 = __builtin_amdgcn_mfma_f32_32x32x16_bf16(vf0, pf, o0, 0, 0, 0);
;             o1 = __builtin_amdgcn_mfma_f32_32x32x16_bf16(vf1, pf, o1, 0, 0, 0);
;         }
	v_mfma_f32_32x32x16_bf16 v[18:33], v[166:169], v[118:121], v[18:33]
	v_mfma_f32_32x32x16_bf16 v[2:17], v[170:173], v[118:121], v[2:17]
	v_cvt_pk_bf16_f32 v118, v214, v215
	v_cvt_pk_bf16_f32 v119, v216, v217
	v_cvt_pk_bf16_f32 v120, v218, v219
	v_cvt_pk_bf16_f32 v121, v220, v221
	v_pk_add_f32 v[214:215], v[214:215], v[216:217]
	v_pk_add_f32 v[218:219], v[218:219], v[220:221]
	v_pk_add_f32 v[214:215], v[214:215], v[218:219]
	v_pk_add_f32 v[116:117], v[116:117], v[214:215]
	v_mfma_f32_32x32x16_bf16 v[18:33], v[174:177], v[118:121], v[18:33]
	v_mfma_f32_32x32x16_bf16 v[2:17], v[178:181], v[118:121], v[2:17]
	v_pk_add_f32 v[222:223], v[222:223], v[114:115] op_sel_hi:[1,0] neg_lo:[0,1] neg_hi:[0,1]
	v_pk_add_f32 v[224:225], v[224:225], v[114:115] op_sel_hi:[1,0] neg_lo:[0,1] neg_hi:[0,1]
	v_pk_add_f32 v[226:227], v[226:227], v[114:115] op_sel_hi:[1,0] neg_lo:[0,1] neg_hi:[0,1]
	v_pk_add_f32 v[228:229], v[228:229], v[114:115] op_sel_hi:[1,0] neg_lo:[0,1] neg_hi:[0,1]
	v_exp_f32_e32 v222, v222
	v_exp_f32_e32 v223, v223
	v_exp_f32_e32 v224, v224
	v_exp_f32_e32 v225, v225
	v_exp_f32_e32 v226, v226
	v_exp_f32_e32 v227, v227
	v_exp_f32_e32 v228, v228
	v_exp_f32_e32 v229, v229
	v_cvt_pk_bf16_f32 v118, v222, v223
	v_cvt_pk_bf16_f32 v119, v224, v225
	v_cvt_pk_bf16_f32 v120, v226, v227
	v_cvt_pk_bf16_f32 v121, v228, v229
	v_pk_add_f32 v[222:223], v[222:223], v[224:225]
	v_pk_add_f32 v[226:227], v[226:227], v[228:229]
	v_pk_add_f32 v[222:223], v[222:223], v[226:227]
	v_pk_add_f32 v[116:117], v[116:117], v[222:223]
	v_mfma_f32_32x32x16_bf16 v[18:33], v[182:185], v[118:121], v[18:33]
	v_mfma_f32_32x32x16_bf16 v[2:17], v[186:189], v[118:121], v[2:17]
	v_pk_add_f32 v[230:231], v[230:231], v[114:115] op_sel_hi:[1,0] neg_lo:[0,1] neg_hi:[0,1]
	v_pk_add_f32 v[232:233], v[232:233], v[114:115] op_sel_hi:[1,0] neg_lo:[0,1] neg_hi:[0,1]
	v_pk_add_f32 v[234:235], v[234:235], v[114:115] op_sel_hi:[1,0] neg_lo:[0,1] neg_hi:[0,1]
	v_pk_add_f32 v[236:237], v[236:237], v[114:115] op_sel_hi:[1,0] neg_lo:[0,1] neg_hi:[0,1]
	v_exp_f32_e32 v230, v230
	v_exp_f32_e32 v231, v231
	v_exp_f32_e32 v232, v232
	v_exp_f32_e32 v233, v233
	v_exp_f32_e32 v234, v234
	v_exp_f32_e32 v235, v235
	v_exp_f32_e32 v236, v236
	v_exp_f32_e32 v237, v237
	v_cvt_pk_bf16_f32 v118, v230, v231
	v_cvt_pk_bf16_f32 v119, v232, v233
	v_cvt_pk_bf16_f32 v120, v234, v235
	v_cvt_pk_bf16_f32 v121, v236, v237
	v_pk_add_f32 v[230:231], v[230:231], v[232:233]
	v_pk_add_f32 v[234:235], v[234:235], v[236:237]
	v_pk_add_f32 v[230:231], v[230:231], v[234:235]
	v_pk_add_f32 v[116:117], v[116:117], v[230:231]
	v_mfma_f32_32x32x16_bf16 v[18:33], v[190:193], v[118:121], v[18:33]
	v_mfma_f32_32x32x16_bf16 v[2:17], v[194:197], v[118:121], v[2:17]
	v_add_f32_e32 v116, v116, v117
	v_add_f32_e32 v109, v109, v116
	s_branch .Lmax_E
.Lqkonly_E:
	s_waitcnt lgkmcnt(9)
	v_mfma_f32_32x32x16_bf16 v[34:49], v[124:127], v[78:81], v[34:49]
	ds_read_b128 v[148:151], v112 offset:8544
	ds_read_b128 v[152:155], v112 offset:13152
	s_waitcnt lgkmcnt(6)
	v_mfma_f32_32x32x16_bf16 v[50:65], v[128:131], v[78:81], v[50:65]
	s_waitcnt lgkmcnt(5)
	v_mfma_f32_32x32x16_bf16 v[34:49], v[132:135], v[74:77], v[34:49]
	s_waitcnt lgkmcnt(4)
	v_mfma_f32_32x32x16_bf16 v[50:65], v[136:139], v[74:77], v[50:65]
	s_waitcnt lgkmcnt(3)
	v_mfma_f32_32x32x16_bf16 v[34:49], v[140:143], v[70:73], v[34:49]
	s_waitcnt lgkmcnt(2)
	v_mfma_f32_32x32x16_bf16 v[50:65], v[144:147], v[70:73], v[50:65]
	s_waitcnt lgkmcnt(1)
	v_mfma_f32_32x32x16_bf16 v[34:49], v[148:151], v[66:69], v[34:49]
	s_waitcnt lgkmcnt(0)
	v_mfma_f32_32x32x16_bf16 v[50:65], v[152:155], v[66:69], v[50:65]
	s_nop 10
.Lmax_E:
	s_add_i32 s7, s6, 63
	s_cmp_gt_i32 s7, s21
	s_cbranch_scc0 .Lnomask_E
	v_add_u32_e32 v115, s6, v100
	v_add_u32_e32 v116, 0, v115
	v_cmp_le_i32_e32 vcc, v116, v110
	s_nop 1
	v_cndmask_b32_e32 v34, v205, v34, vcc
	v_add_u32_e32 v116, 1, v115
	v_cmp_le_i32_e32 vcc, v116, v110
	s_nop 1
	v_cndmask_b32_e32 v35, v205, v35, vcc
	v_add_u32_e32 v116, 2, v115
	v_cmp_le_i32_e32 vcc, v116, v110
	s_nop 1
	v_cndmask_b32_e32 v36, v205, v36, vcc
	v_add_u32_e32 v116, 3, v115
	v_cmp_le_i32_e32 vcc, v116, v110
	s_nop 1
	v_cndmask_b32_e32 v37, v205, v37, vcc
	v_add_u32_e32 v116, 8, v115
	v_cmp_le_i32_e32 vcc, v116, v110
	s_nop 1
	v_cndmask_b32_e32 v38, v205, v38, vcc
	v_add_u32_e32 v116, 9, v115
	v_cmp_le_i32_e32 vcc, v116, v110
	s_nop 1
	v_cndmask_b32_e32 v39, v205, v39, vcc
	v_add_u32_e32 v116, 10, v115
	v_cmp_le_i32_e32 vcc, v116, v110
	s_nop 1
	v_cndmask_b32_e32 v40, v205, v40, vcc
	v_add_u32_e32 v116, 11, v115
	v_cmp_le_i32_e32 vcc, v116, v110
	s_nop 1
	v_cndmask_b32_e32 v41, v205, v41, vcc
	v_add_u32_e32 v116, 16, v115
	v_cmp_le_i32_e32 vcc, v116, v110
	s_nop 1
	v_cndmask_b32_e32 v42, v205, v42, vcc
	v_add_u32_e32 v116, 17, v115
	v_cmp_le_i32_e32 vcc, v116, v110
	s_nop 1
	v_cndmask_b32_e32 v43, v205, v43, vcc
	v_add_u32_e32 v116, 18, v115
	v_cmp_le_i32_e32 vcc, v116, v110
	s_nop 1
	v_cndmask_b32_e32 v44, v205, v44, vcc
	v_add_u32_e32 v116, 19, v115
	v_cmp_le_i32_e32 vcc, v116, v110
	s_nop 1
	v_cndmask_b32_e32 v45, v205, v45, vcc
	v_add_u32_e32 v116, 24, v115
	v_cmp_le_i32_e32 vcc, v116, v110
	s_nop 1
	v_cndmask_b32_e32 v46, v205, v46, vcc
	v_add_u32_e32 v116, 25, v115
	v_cmp_le_i32_e32 vcc, v116, v110
	s_nop 1
	v_cndmask_b32_e32 v47, v205, v47, vcc
	v_add_u32_e32 v116, 26, v115
	v_cmp_le_i32_e32 vcc, v116, v110
	s_nop 1
	v_cndmask_b32_e32 v48, v205, v48, vcc
	v_add_u32_e32 v116, 27, v115
	v_cmp_le_i32_e32 vcc, v116, v110
	s_nop 1
	v_cndmask_b32_e32 v49, v205, v49, vcc
	v_add_u32_e32 v116, 32, v115
	v_cmp_le_i32_e32 vcc, v116, v110
	s_nop 1
	v_cndmask_b32_e32 v50, v205, v50, vcc
	v_add_u32_e32 v116, 33, v115
; __device__ __forceinline__ float fexp2(float x) { return __builtin_amdgcn_exp2f(x); }
; __device__ __forceinline__ int crow(int r, int hi) { return (r & 3) + 8 * (r >> 2) + 4 * hi; }
; __device__ __forceinline__ void attn_tile(int t, int buf, LAS unsigned char* lds, const bf16x8 (&qr)[4], float cq2, int qlo, int qpos, int q32, int hi,
;                                           float& mrun, float& lrun, f32x16& o0, f32x16& o1) {
;     ...
;     if (64 * t + 63 > qlo) {
; #pragma unroll
;         for (int r = 0; r < 16; ++r) { const int kv = 64 * t + crow(r, hi); if (kv > qpos) s0[r] = -INFINITY; if (kv + 32 > qpos) s1[r] = -INFINITY; }
;     }
;     float mx = fmaxf(s0[0], s1[0]);
; #pragma unroll
;     for (int r = 1; r < 16; ++r) mx = fmaxf(mx, fmaxf(s0[r], s1[r]));
;     mx = fmaxf(mx, __shfl_xor(mx, 32));
;     const float mnew = fmaxf(mrun, mx);
;     if (__any(mnew > mrun)) {
;         const float alpha = fexp2(mrun - mnew); lrun *= alpha;
; #pragma unroll
;         for (int r = 0; r < 16; ++r) { o0[r] *= alpha; o1[r] *= alpha; }
;     }
;     mrun = mnew;
;     f32x2 ls2 = (f32x2){0.f, 0.f};
; #pragma unroll
;     for (int r = 0; r < 16; r += 2) {
;         const f32x2 d0 = (f32x2){s0[r], s0[r + 1]} - mnew, d1 = (f32x2){s1[r], s1[r + 1]} - mnew;
;         f32x2 e0, e1; e0.x = fexp2(d0.x); e0.y = fexp2(d0.y); e1.x = fexp2(d1.x); e1.y = fexp2(d1.y);
;         s0[r] = e0.x; s0[r + 1] = e0.y; s1[r] = e1.x; s1[r + 1] = e1.y;
;         ls2 += e0 + e1;
;     }
;     lrun += ls2.x + ls2.y;
	v_cmp_le_i32_e32 vcc, v116, v110
	s_nop 1
	v_cndmask_b32_e32 v51, v205, v51, vcc
	v_add_u32_e32 v116, 34, v115
	v_cmp_le_i32_e32 vcc, v116, v110
	s_nop 1
	v_cndmask_b32_e32 v52, v205, v52, vcc
	v_add_u32_e32 v116, 35, v115
	v_cmp_le_i32_e32 vcc, v116, v110
	s_nop 1
	v_cndmask_b32_e32 v53, v205, v53, vcc
	v_add_u32_e32 v116, 40, v115
	v_cmp_le_i32_e32 vcc, v116, v110
	s_nop 1
	v_cndmask_b32_e32 v54, v205, v54, vcc
	v_add_u32_e32 v116, 41, v115
	v_cmp_le_i32_e32 vcc, v116, v110
	s_nop 1
	v_cndmask_b32_e32 v55, v205, v55, vcc
	v_add_u32_e32 v116, 42, v115
	v_cmp_le_i32_e32 vcc, v116, v110
	s_nop 1
	v_cndmask_b32_e32 v56, v205, v56, vcc
	v_add_u32_e32 v116, 43, v115
	v_cmp_le_i32_e32 vcc, v116, v110
	s_nop 1
	v_cndmask_b32_e32 v57, v205, v57, vcc
	v_add_u32_e32 v116, 48, v115
	v_cmp_le_i32_e32 vcc, v116, v110
	s_nop 1
	v_cndmask_b32_e32 v58, v205, v58, vcc
	v_add_u32_e32 v116, 49, v115
	v_cmp_le_i32_e32 vcc, v116, v110
	s_nop 1
	v_cndmask_b32_e32 v59, v205, v59, vcc
	v_add_u32_e32 v116, 50, v115
	v_cmp_le_i32_e32 vcc, v116, v110
	s_nop 1
	v_cndmask_b32_e32 v60, v205, v60, vcc
	v_add_u32_e32 v116, 51, v115
	v_cmp_le_i32_e32 vcc, v116, v110
	s_nop 1
	v_cndmask_b32_e32 v61, v205, v61, vcc
	v_add_u32_e32 v116, 56, v115
	v_cmp_le_i32_e32 vcc, v116, v110
	s_nop 1
	v_cndmask_b32_e32 v62, v205, v62, vcc
	v_add_u32_e32 v116, 57, v115
	v_cmp_le_i32_e32 vcc, v116, v110
	s_nop 1
	v_cndmask_b32_e32 v63, v205, v63, vcc
	v_add_u32_e32 v116, 58, v115
	v_cmp_le_i32_e32 vcc, v116, v110
	s_nop 1
	v_cndmask_b32_e32 v64, v205, v64, vcc
	v_add_u32_e32 v116, 59, v115
	v_cmp_le_i32_e32 vcc, v116, v110
	s_nop 1
	v_cndmask_b32_e32 v65, v205, v65, vcc
.Lnomask_E:
	v_max3_f32 v0, v34, v50, v35
	v_max3_f32 v115, v51, v36, v52
	v_max3_f32 v0, v0, v37, v53
	v_max3_f32 v115, v115, v38, v54
	v_max3_f32 v0, v0, v39, v55
	v_max3_f32 v115, v115, v40, v56
	v_max3_f32 v0, v0, v41, v57
	v_max3_f32 v115, v115, v42, v58
	v_max3_f32 v0, v0, v43, v59
	v_max3_f32 v115, v115, v44, v60
	v_max3_f32 v0, v0, v45, v61
	v_max3_f32 v115, v115, v46, v62
	v_max3_f32 v0, v0, v47, v63
	v_max3_f32 v115, v115, v48, v64
	v_max3_f32 v0, v0, v49, v65
	v_max_f32_e32 v0, v0, v115
	ds_bpermute_b32 v115, v107, v0
	s_waitcnt lgkmcnt(0)
	v_max3_f32 v0, v114, v0, v115
	v_add_f32_e32 v115, 0x41c00000, v114
	v_cmp_gt_f32_e32 vcc, v0, v115
	s_cbranch_vccz .Lnoresc_E
	v_sub_f32_e32 v114, v114, v0
	v_exp_f32_e32 v114, v114
	s_nop 0
	v_mul_f32_e32 v109, v109, v114
	v_pk_mul_f32 v[32:33], v[32:33], v[114:115] op_sel_hi:[1,0]
	v_pk_mul_f32 v[30:31], v[30:31], v[114:115] op_sel_hi:[1,0]
	v_pk_mul_f32 v[28:29], v[28:29], v[114:115] op_sel_hi:[1,0]
	v_pk_mul_f32 v[26:27], v[26:27], v[114:115] op_sel_hi:[1,0]
	v_pk_mul_f32 v[24:25], v[24:25], v[114:115] op_sel_hi:[1,0]
	v_pk_mul_f32 v[22:23], v[22:23], v[114:115] op_sel_hi:[1,0]
	v_pk_mul_f32 v[20:21], v[20:21], v[114:115] op_sel_hi:[1,0]
	v_pk_mul_f32 v[18:19], v[18:19], v[114:115] op_sel_hi:[1,0]
	v_pk_mul_f32 v[16:17], v[16:17], v[114:115] op_sel_hi:[1,0]
	v_pk_mul_f32 v[14:15], v[14:15], v[114:115] op_sel_hi:[1,0]
	v_pk_mul_f32 v[12:13], v[12:13], v[114:115] op_sel_hi:[1,0]
	v_pk_mul_f32 v[10:11], v[10:11], v[114:115] op_sel_hi:[1,0]
	v_pk_mul_f32 v[8:9], v[8:9], v[114:115] op_sel_hi:[1,0]
	v_pk_mul_f32 v[6:7], v[6:7], v[114:115] op_sel_hi:[1,0]
	v_pk_mul_f32 v[4:5], v[4:5], v[114:115] op_sel_hi:[1,0]
	v_pk_mul_f32 v[2:3], v[2:3], v[114:115] op_sel_hi:[1,0]
	v_mov_b32_e32 v114, v0
.Lnoresc_E:
	s_mov_b32 s26, 1
	s_branch .Lend_E
.Lnoproc_E:
	s_mov_b32 s26, 0
	s_cmp_eq_u32 s27, 0
	s_cbranch_scc1 .Lend_E
	v_add_u32_e32 v122, 0x8800, v113
	v_add_u32_e32 v123, 0x9800, v113
	ds_read2_b64 v[166:169], v122 offset0:96 offset1:98
	ds_read2_b64 v[170:173], v123 offset0:128 offset1:130
	ds_read2_b64 v[174:177], v122 offset0:100 offset1:102
	ds_read2_b64 v[178:181], v123 offset0:132 offset1:134
	ds_read2_b64 v[182:185], v122 offset0:104 offset1:106
	ds_read2_b64 v[186:189], v123 offset0:136 offset1:138
	ds_read2_b64 v[190:193], v122 offset0:108 offset1:110
	ds_read2_b64 v[194:197], v123 offset0:140 offset1:142
	v_pk_add_f32 v[206:207], v[206:207], v[114:115] op_sel_hi:[1,0] neg_lo:[0,1] neg_hi:[0,1]
	v_pk_add_f32 v[208:209], v[208:209], v[114:115] op_sel_hi:[1,0] neg_lo:[0,1] neg_hi:[0,1]
	v_pk_add_f32 v[210:211], v[210:211], v[114:115] op_sel_hi:[1,0] neg_lo:[0,1] neg_hi:[0,1]
	v_pk_add_f32 v[212:213], v[212:213], v[114:115] op_sel_hi:[1,0] neg_lo:[0,1] neg_hi:[0,1]
	v_exp_f32_e32 v206, v206
	v_exp_f32_e32 v207, v207
	v_exp_f32_e32 v208, v208
	v_exp_f32_e32 v209, v209
	v_exp_f32_e32 v210, v210
	v_exp_f32_e32 v211, v211
	v_exp_f32_e32 v212, v212
	v_exp_f32_e32 v213, v213
	v_cvt_pk_bf16_f32 v118, v206, v207
	v_cvt_pk_bf16_f32 v119, v208, v209
	v_cvt_pk_bf16_f32 v120, v210, v211
	v_cvt_pk_bf16_f32 v121, v212, v213
	v_pk_add_f32 v[116:117], v[206:207], v[208:209]
	v_pk_add_f32 v[210:211], v[210:211], v[212:213]
	v_pk_add_f32 v[116:117], v[116:117], v[210:211]
	s_waitcnt lgkmcnt(0)
; __device__ __forceinline__ void attn_tile(int t, int buf, LAS unsigned char* lds, const bf16x8 (&qr)[4], float cq2, int qlo, int qpos, int q32, int hi,
;                                           float& mrun, float& lrun, f32x16& o0, f32x16& o1) {
;     ...
;     f32x2 ls2 = (f32x2){0.f, 0.f};
; #pragma unroll
;     for (int r = 0; r < 16; r += 2) {
;         const f32x2 d0 = (f32x2){s0[r], s0[r + 1]} - mnew, d1 = (f32x2){s1[r], s1[r + 1]} - mnew;
;         f32x2 e0, e1; e0.x = fexp2(d0.x); e0.y = fexp2(d0.y); e1.x = fexp2(d1.x); e1.y = fexp2(d1.y);
;         s0[r] = e0.x; s0[r + 1] = e0.y; s1[r] = e1.x; s1[r + 1] = e1.y;
;         ls2 += e0 + e1;
;     }
;     lrun += ls2.x + ls2.y;
; #pragma unroll
;     for (int p = 0; p < 2; ++p)
; #pragma unroll
;         for (int sx = 0; sx < 2; ++sx) {
;             u32x4 pw;
;             if (p == 0) pw = (u32x4){pk_bf16(s0[8 * sx + 0], s0[8 * sx + 1]), pk_bf16(s0[8 * sx + 2], s0[8 * sx + 3]), pk_bf16(s0[8 * sx + 4], s0[8 * sx + 5]), pk_bf16(s0[8 * sx + 6], s0[8 * sx + 7])};
;             else        pw = (u32x4){pk_bf16(s1[8 * sx + 0], s1[8 * sx + 1]), pk_bf16(s1[8 * sx + 2], s1[8 * sx + 3]), pk_bf16(s1[8 * sx + 4], s1[8 * sx + 5]), pk_bf16(s1[8 * sx + 6], s1[8 * sx + 7])};
;             const bf16x8 pf = __builtin_bit_cast(bf16x8, pw);
;             const int ko = (32 * p + 16 * sx + 4 * hi) * 2;
;             const u32x2 a0 = *(const LAS u32x2*)(Vt + q32 * 136 + ko), a1 = *(const LAS u32x2*)(Vt + q32 * 136 + ko + 16);
;             const u32x2 b0 = *(const LAS u32x2*)(Vt + (32 + q32) * 136 + ko), b1 = *(const LAS u32x2*)(Vt + (32 + q32) * 136 + ko + 16);
;             const bf16x8 vf0 = __builtin_bit_cast(bf16x8, (u32x4){a0.x, a0.y, a1.x, a1.y});
;             const bf16x8 vf1 = __builtin_bit_cast(bf16x8, (u32x4){b0.x, b0.y, b1.x, b1.y});
;             o0 = __builtin_amdgcn_mfma_f32_32x32x16_bf16(vf0, pf, o0, 0, 0, 0);
;             o1 = __builtin_amdgcn_mfma_f32_32x32x16_bf16(vf1, pf, o1, 0, 0, 0);
;         }
; __device__ __forceinline__ void attn_unit(const AttnJob& J, LAS unsigned char* lds) {
;     ...
;     for (int t = 0; t < J.NT; t += 2) {
;         attn_stage(lds, 0, kA, vA);
;         __syncthreads();
;         if (t + 2 < J.NT) attn_load(J, t + 2, kA, vA);
;         if (active && 64 * t <= qlo + 31) attn_tile(t, 0, lds, qr, cq2, qlo, qpos, q32, hi, mrun, lrun, o0, o1);
;         if (t + 1 < J.NT) {
	v_mfma_f32_32x32x16_bf16 v[18:33], v[166:169], v[118:121], v[18:33]
	v_mfma_f32_32x32x16_bf16 v[2:17], v[170:173], v[118:121], v[2:17]
	v_pk_add_f32 v[214:215], v[214:215], v[114:115] op_sel_hi:[1,0] neg_lo:[0,1] neg_hi:[0,1]
	v_pk_add_f32 v[216:217], v[216:217], v[114:115] op_sel_hi:[1,0] neg_lo:[0,1] neg_hi:[0,1]
	v_pk_add_f32 v[218:219], v[218:219], v[114:115] op_sel_hi:[1,0] neg_lo:[0,1] neg_hi:[0,1]
	v_pk_add_f32 v[220:221], v[220:221], v[114:115] op_sel_hi:[1,0] neg_lo:[0,1] neg_hi:[0,1]
	v_exp_f32_e32 v214, v214
	v_exp_f32_e32 v215, v215
	v_exp_f32_e32 v216, v216
	v_exp_f32_e32 v217, v217
	v_exp_f32_e32 v218, v218
	v_exp_f32_e32 v219, v219
	v_exp_f32_e32 v220, v220
	v_exp_f32_e32 v221, v221
	v_cvt_pk_bf16_f32 v118, v214, v215
	v_cvt_pk_bf16_f32 v119, v216, v217
	v_cvt_pk_bf16_f32 v120, v218, v219
	v_cvt_pk_bf16_f32 v121, v220, v221
	v_pk_add_f32 v[214:215], v[214:215], v[216:217]
	v_pk_add_f32 v[218:219], v[218:219], v[220:221]
	v_pk_add_f32 v[214:215], v[214:215], v[218:219]
	v_pk_add_f32 v[116:117], v[116:117], v[214:215]
	v_mfma_f32_32x32x16_bf16 v[18:33], v[174:177], v[118:121], v[18:33]
	v_mfma_f32_32x32x16_bf16 v[2:17], v[178:181], v[118:121], v[2:17]
	v_pk_add_f32 v[222:223], v[222:223], v[114:115] op_sel_hi:[1,0] neg_lo:[0,1] neg_hi:[0,1]
	v_pk_add_f32 v[224:225], v[224:225], v[114:115] op_sel_hi:[1,0] neg_lo:[0,1] neg_hi:[0,1]
	v_pk_add_f32 v[226:227], v[226:227], v[114:115] op_sel_hi:[1,0] neg_lo:[0,1] neg_hi:[0,1]
	v_pk_add_f32 v[228:229], v[228:229], v[114:115] op_sel_hi:[1,0] neg_lo:[0,1] neg_hi:[0,1]
	v_exp_f32_e32 v222, v222
	v_exp_f32_e32 v223, v223
	v_exp_f32_e32 v224, v224
	v_exp_f32_e32 v225, v225
	v_exp_f32_e32 v226, v226
	v_exp_f32_e32 v227, v227
	v_exp_f32_e32 v228, v228
	v_exp_f32_e32 v229, v229
	v_cvt_pk_bf16_f32 v118, v222, v223
	v_cvt_pk_bf16_f32 v119, v224, v225
	v_cvt_pk_bf16_f32 v120, v226, v227
	v_cvt_pk_bf16_f32 v121, v228, v229
	v_pk_add_f32 v[222:223], v[222:223], v[224:225]
	v_pk_add_f32 v[226:227], v[226:227], v[228:229]
	v_pk_add_f32 v[222:223], v[222:223], v[226:227]
	v_pk_add_f32 v[116:117], v[116:117], v[222:223]
	v_mfma_f32_32x32x16_bf16 v[18:33], v[182:185], v[118:121], v[18:33]
	v_mfma_f32_32x32x16_bf16 v[2:17], v[186:189], v[118:121], v[2:17]
	v_pk_add_f32 v[230:231], v[230:231], v[114:115] op_sel_hi:[1,0] neg_lo:[0,1] neg_hi:[0,1]
	v_pk_add_f32 v[232:233], v[232:233], v[114:115] op_sel_hi:[1,0] neg_lo:[0,1] neg_hi:[0,1]
	v_pk_add_f32 v[234:235], v[234:235], v[114:115] op_sel_hi:[1,0] neg_lo:[0,1] neg_hi:[0,1]
	v_pk_add_f32 v[236:237], v[236:237], v[114:115] op_sel_hi:[1,0] neg_lo:[0,1] neg_hi:[0,1]
	v_exp_f32_e32 v230, v230
	v_exp_f32_e32 v231, v231
	v_exp_f32_e32 v232, v232
	v_exp_f32_e32 v233, v233
	v_exp_f32_e32 v234, v234
	v_exp_f32_e32 v235, v235
	v_exp_f32_e32 v236, v236
	v_exp_f32_e32 v237, v237
	v_cvt_pk_bf16_f32 v118, v230, v231
	v_cvt_pk_bf16_f32 v119, v232, v233
	v_cvt_pk_bf16_f32 v120, v234, v235
	v_cvt_pk_bf16_f32 v121, v236, v237
	v_pk_add_f32 v[230:231], v[230:231], v[232:233]
	v_pk_add_f32 v[234:235], v[234:235], v[236:237]
	v_pk_add_f32 v[230:231], v[230:231], v[234:235]
	v_pk_add_f32 v[116:117], v[116:117], v[230:231]
	v_mfma_f32_32x32x16_bf16 v[18:33], v[190:193], v[118:121], v[18:33]
	v_mfma_f32_32x32x16_bf16 v[2:17], v[194:197], v[118:121], v[2:17]
	v_add_f32_e32 v116, v116, v117
	v_add_f32_e32 v109, v109, v116
.Lend_E:
.Lslot_O:
	s_waitcnt vmcnt(2)
	ds_write_b128 v156, v[90:93] offset:17664
	ds_write_b16 v157, v86 offset:26880
	ds_write_b16_d16_hi v157, v86 offset:27016
	ds_write_b16 v157, v87 offset:27152
	ds_write_b16_d16_hi v157, v87 offset:27288
	ds_write_b16 v157, v88 offset:27424
	ds_write_b16_d16_hi v157, v88 offset:27560
	ds_write_b16 v157, v89 offset:27696
	ds_write_b16_d16_hi v157, v89 offset:27832
	s_waitcnt lgkmcnt(0)
	s_barrier
	s_add_i32 s6, s22, 3
	s_lshl_b32 s6, s6, 18
	s_add_u32 s98, s8, s6
	s_addc_u32 s99, s9, 0
	global_load_dwordx4 v[90:93], v158, s[98:99] offset:1024
	s_sub_u32 s100, s98, 0x40000
	s_subb_u32 s101, s99, 0
	global_load_dwordx4 v[86:89], v158, s[100:101] offset:2048
	s_lshl_b32 s6, s22, 6
	s_add_i32 s6, s6, 64
	s_cmp_le_i32 s6, s23
	s_cbranch_scc0 .Lnoproc_O
	ds_read_b128 v[124:127], v112 offset:17664
	ds_read_b128 v[206:209], v111 offset:256
	ds_read_b128 v[210:213], v111 offset:288
	ds_read_b128 v[214:217], v111 offset:320
	ds_read_b128 v[218:221], v111 offset:352
	ds_read_b128 v[128:131], v112 offset:22272
	ds_read_b128 v[222:225], v111 offset:384
	ds_read_b128 v[226:229], v111 offset:416
	ds_read_b128 v[230:233], v111 offset:448
	ds_read_b128 v[234:237], v111 offset:480
	ds_read_b128 v[132:135], v112 offset:17696
	ds_read_b128 v[136:139], v112 offset:22304
	ds_read_b128 v[140:143], v112 offset:17728
	ds_read_b128 v[144:147], v112 offset:22336
	s_cmp_eq_u32 s26, 0
	s_cbranch_scc1 .Lqkonly_O
; __device__ __forceinline__ void attn_tile(int t, int buf, LAS unsigned char* lds, const bf16x8 (&qr)[4], float cq2, int qlo, int qpos, int q32, int hi,
;                                           float& mrun, float& lrun, f32x16& o0, f32x16& o1) {
;     ...
; #pragma unroll
;     for (int d0 = 0; d0 < 4; ++d0) {
;         const bf16x8 k0 = *(const LAS bf16x8*)(Kt + q32 * 144 + d0 * 32 + hi * 16);
;         const bf16x8 k1 = *(const LAS bf16x8*)(Kt + (32 + q32) * 144 + d0 * 32 + hi * 16);
;         s0 = __builtin_amdgcn_mfma_f32_32x32x16_bf16(k0, qr[d0], s0, 0, 0, 0);
;         s1 = __builtin_amdgcn_mfma_f32_32x32x16_bf16(k1, qr[d0], s1, 0, 0, 0);
;     }
;     ...
;     f32x2 ls2 = (f32x2){0.f, 0.f};
; #pragma unroll
;     for (int r = 0; r < 16; r += 2) {
;         const f32x2 d0 = (f32x2){s0[r], s0[r + 1]} - mnew, d1 = (f32x2){s1[r], s1[r + 1]} - mnew;
;         f32x2 e0, e1; e0.x = fexp2(d0.x); e0.y = fexp2(d0.y); e1.x = fexp2(d1.x); e1.y = fexp2(d1.y);
;         s0[r] = e0.x; s0[r + 1] = e0.y; s1[r] = e1.x; s1[r + 1] = e1.y;
;         ls2 += e0 + e1;
;     }
;     lrun += ls2.x + ls2.y;
; #pragma unroll
;     for (int p = 0; p < 2; ++p)
; #pragma unroll
;         for (int sx = 0; sx < 2; ++sx) {
;             u32x4 pw;
;             if (p == 0) pw = (u32x4){pk_bf16(s0[8 * sx + 0], s0[8 * sx + 1]), pk_bf16(s0[8 * sx + 2], s0[8 * sx + 3]), pk_bf16(s0[8 * sx + 4], s0[8 * sx + 5]), pk_bf16(s0[8 * sx + 6], s0[8 * sx + 7])};
;             else        pw = (u32x4){pk_bf16(s1[8 * sx + 0], s1[8 * sx + 1]), pk_bf16(s1[8 * sx + 2], s1[8 * sx + 3]), pk_bf16(s1[8 * sx + 4], s1[8 * sx + 5]), pk_bf16(s1[8 * sx + 6], s1[8 * sx + 7])};
;             const bf16x8 pf = __builtin_bit_cast(bf16x8, pw);
;             const int ko = (32 * p + 16 * sx + 4 * hi) * 2;
;             const u32x2 a0 = *(const LAS u32x2*)(Vt + q32 * 136 + ko), a1 = *(const LAS u32x2*)(Vt + q32 * 136 + ko + 16);
;             const u32x2 b0 = *(const LAS u32x2*)(Vt + (32 + q32) * 136 + ko), b1 = *(const LAS u32x2*)(Vt + (32 + q32) * 136 + ko + 16);
;             const bf16x8 vf0 = __builtin_bit_cast(bf16x8, (u32x4){a0.x, a0.y, a1.x, a1.y});
;             const bf16x8 vf1 = __builtin_bit_cast(bf16x8, (u32x4){b0.x, b0.y, b1.x, b1.y});
;             o0 = __builtin_amdgcn_mfma_f32_32x32x16_bf16(vf0, pf, o0, 0, 0, 0);
;             o1 = __builtin_amdgcn_mfma_f32_32x32x16_bf16(vf1, pf, o1, 0, 0, 0);
;         }
	v_pk_add_f32 v[34:35], v[34:35], v[114:115] op_sel_hi:[1,0] neg_lo:[0,1] neg_hi:[0,1]
	v_pk_add_f32 v[36:37], v[36:37], v[114:115] op_sel_hi:[1,0] neg_lo:[0,1] neg_hi:[0,1]
	v_pk_add_f32 v[38:39], v[38:39], v[114:115] op_sel_hi:[1,0] neg_lo:[0,1] neg_hi:[0,1]
	v_pk_add_f32 v[40:41], v[40:41], v[114:115] op_sel_hi:[1,0] neg_lo:[0,1] neg_hi:[0,1]
	v_exp_f32_e32 v34, v34
	v_exp_f32_e32 v35, v35
	v_exp_f32_e32 v36, v36
	v_exp_f32_e32 v37, v37
	v_exp_f32_e32 v38, v38
	v_exp_f32_e32 v39, v39
	v_exp_f32_e32 v40, v40
	v_exp_f32_e32 v41, v41
	v_cvt_pk_bf16_f32 v118, v34, v35
	v_cvt_pk_bf16_f32 v119, v36, v37
	v_cvt_pk_bf16_f32 v120, v38, v39
	v_cvt_pk_bf16_f32 v121, v40, v41
	v_pk_add_f32 v[116:117], v[34:35], v[36:37]
	v_pk_add_f32 v[38:39], v[38:39], v[40:41]
	v_pk_add_f32 v[116:117], v[116:117], v[38:39]
	s_waitcnt lgkmcnt(9)
	v_mfma_f32_32x32x16_bf16 v[206:221], v[124:127], v[78:81], v[206:221]
	ds_read_b128 v[148:151], v112 offset:17760
	ds_read_b128 v[152:155], v112 offset:22368
	s_waitcnt lgkmcnt(6)
	v_mfma_f32_32x32x16_bf16 v[222:237], v[128:131], v[78:81], v[222:237]
	s_waitcnt lgkmcnt(5)
	v_mfma_f32_32x32x16_bf16 v[206:221], v[132:135], v[74:77], v[206:221]
	s_waitcnt lgkmcnt(4)
	v_mfma_f32_32x32x16_bf16 v[222:237], v[136:139], v[74:77], v[222:237]
	s_waitcnt lgkmcnt(3)
	v_mfma_f32_32x32x16_bf16 v[206:221], v[140:143], v[70:73], v[206:221]
	s_waitcnt lgkmcnt(2)
	v_mfma_f32_32x32x16_bf16 v[222:237], v[144:147], v[70:73], v[222:237]
	s_waitcnt lgkmcnt(1)
	v_mfma_f32_32x32x16_bf16 v[206:221], v[148:151], v[66:69], v[206:221]
	s_waitcnt lgkmcnt(0)
	v_mfma_f32_32x32x16_bf16 v[222:237], v[152:155], v[66:69], v[222:237]
	v_add_u32_e32 v122, 0x6800, v113
	v_add_u32_e32 v123, 0x7800, v113
	ds_read2_b64 v[166:169], v122 offset0:32 offset1:34
	ds_read2_b64 v[170:173], v123 offset0:64 offset1:66
	ds_read2_b64 v[174:177], v122 offset0:36 offset1:38
	ds_read2_b64 v[178:181], v123 offset0:68 offset1:70
	ds_read2_b64 v[182:185], v122 offset0:40 offset1:42
	ds_read2_b64 v[186:189], v123 offset0:72 offset1:74
	ds_read2_b64 v[190:193], v122 offset0:44 offset1:46
	ds_read2_b64 v[194:197], v123 offset0:76 offset1:78
	v_pk_add_f32 v[42:43], v[42:43], v[114:115] op_sel_hi:[1,0] neg_lo:[0,1] neg_hi:[0,1]
	v_pk_add_f32 v[44:45], v[44:45], v[114:115] op_sel_hi:[1,0] neg_lo:[0,1] neg_hi:[0,1]
	v_pk_add_f32 v[46:47], v[46:47], v[114:115] op_sel_hi:[1,0] neg_lo:[0,1] neg_hi:[0,1]
	v_pk_add_f32 v[48:49], v[48:49], v[114:115] op_sel_hi:[1,0] neg_lo:[0,1] neg_hi:[0,1]
	v_exp_f32_e32 v42, v42
	v_exp_f32_e32 v43, v43
	v_exp_f32_e32 v44, v44
	v_exp_f32_e32 v45, v45
	v_exp_f32_e32 v46, v46
	v_exp_f32_e32 v47, v47
	v_exp_f32_e32 v48, v48
	v_exp_f32_e32 v49, v49
	s_waitcnt lgkmcnt(0)
	v_mfma_f32_32x32x16_bf16 v[18:33], v[166:169], v[118:121], v[18:33]
	v_mfma_f32_32x32x16_bf16 v[2:17], v[170:173], v[118:121], v[2:17]
	v_cvt_pk_bf16_f32 v118, v42, v43
	v_cvt_pk_bf16_f32 v119, v44, v45
	v_cvt_pk_bf16_f32 v120, v46, v47
	v_cvt_pk_bf16_f32 v121, v48, v49
	v_pk_add_f32 v[42:43], v[42:43], v[44:45]
	v_pk_add_f32 v[46:47], v[46:47], v[48:49]
	v_pk_add_f32 v[42:43], v[42:43], v[46:47]
	v_pk_add_f32 v[116:117], v[116:117], v[42:43]
	v_mfma_f32_32x32x16_bf16 v[18:33], v[174:177], v[118:121], v[18:33]
	v_mfma_f32_32x32x16_bf16 v[2:17], v[178:181], v[118:121], v[2:17]
	v_pk_add_f32 v[50:51], v[50:51], v[114:115] op_sel_hi:[1,0] neg_lo:[0,1] neg_hi:[0,1]
	v_pk_add_f32 v[52:53], v[52:53], v[114:115] op_sel_hi:[1,0] neg_lo:[0,1] neg_hi:[0,1]
	v_pk_add_f32 v[54:55], v[54:55], v[114:115] op_sel_hi:[1,0] neg_lo:[0,1] neg_hi:[0,1]
	v_pk_add_f32 v[56:57], v[56:57], v[114:115] op_sel_hi:[1,0] neg_lo:[0,1] neg_hi:[0,1]
	v_exp_f32_e32 v50, v50
	v_exp_f32_e32 v51, v51
	v_exp_f32_e32 v52, v52
	v_exp_f32_e32 v53, v53
	v_exp_f32_e32 v54, v54
	v_exp_f32_e32 v55, v55
	v_exp_f32_e32 v56, v56
	v_exp_f32_e32 v57, v57
	v_cvt_pk_bf16_f32 v118, v50, v51
	v_cvt_pk_bf16_f32 v119, v52, v53
	v_cvt_pk_bf16_f32 v120, v54, v55
	v_cvt_pk_bf16_f32 v121, v56, v57
	v_pk_add_f32 v[50:51], v[50:51], v[52:53]
	v_pk_add_f32 v[54:55], v[54:55], v[56:57]
	v_pk_add_f32 v[50:51], v[50:51], v[54:55]
	v_pk_add_f32 v[116:117], v[116:117], v[50:51]
	v_mfma_f32_32x32x16_bf16 v[18:33], v[182:185], v[118:121], v[18:33]
	v_mfma_f32_32x32x16_bf16 v[2:17], v[186:189], v[118:121], v[2:17]
	v_pk_add_f32 v[58:59], v[58:59], v[114:115] op_sel_hi:[1,0] neg_lo:[0,1] neg_hi:[0,1]
	v_pk_add_f32 v[60:61], v[60:61], v[114:115] op_sel_hi:[1,0] neg_lo:[0,1] neg_hi:[0,1]
	v_pk_add_f32 v[62:63], v[62:63], v[114:115] op_sel_hi:[1,0] neg_lo:[0,1] neg_hi:[0,1]
	v_pk_add_f32 v[64:65], v[64:65], v[114:115] op_sel_hi:[1,0] neg_lo:[0,1] neg_hi:[0,1]
	v_exp_f32_e32 v58, v58
	v_exp_f32_e32 v59, v59
	v_exp_f32_e32 v60, v60
	v_exp_f32_e32 v61, v61
	v_exp_f32_e32 v62, v62
	v_exp_f32_e32 v63, v63
	v_exp_f32_e32 v64, v64
	v_exp_f32_e32 v65, v65
	v_cvt_pk_bf16_f32 v118, v58, v59
	v_cvt_pk_bf16_f32 v119, v60, v61
	v_cvt_pk_bf16_f32 v120, v62, v63
	v_cvt_pk_bf16_f32 v121, v64, v65
	v_pk_add_f32 v[58:59], v[58:59], v[60:61]
	v_pk_add_f32 v[62:63], v[62:63], v[64:65]
	v_pk_add_f32 v[58:59], v[58:59], v[62:63]
	v_pk_add_f32 v[116:117], v[116:117], v[58:59]
	v_mfma_f32_32x32x16_bf16 v[18:33], v[190:193], v[118:121], v[18:33]
	v_mfma_f32_32x32x16_bf16 v[2:17], v[194:197], v[118:121], v[2:17]
	v_add_f32_e32 v116, v116, v117
	v_add_f32_e32 v109, v109, v116
	s_branch .Lmax_O
; #define LAS __attribute__((address_space(3)))
; __device__ __forceinline__ float fexp2(float x) { return __builtin_amdgcn_exp2f(x); }
; __device__ __forceinline__ int crow(int r, int hi) { return (r & 3) + 8 * (r >> 2) + 4 * hi; }
; __device__ __forceinline__ void attn_tile(int t, int buf, LAS unsigned char* lds, const bf16x8 (&qr)[4], float cq2, int qlo, int qpos, int q32, int hi,
;                                           float& mrun, float& lrun, f32x16& o0, f32x16& o1) {
;     ...
; #pragma unroll
;     for (int d0 = 0; d0 < 4; ++d0) {
;         const bf16x8 k0 = *(const LAS bf16x8*)(Kt + q32 * 144 + d0 * 32 + hi * 16);
;         const bf16x8 k1 = *(const LAS bf16x8*)(Kt + (32 + q32) * 144 + d0 * 32 + hi * 16);
;         s0 = __builtin_amdgcn_mfma_f32_32x32x16_bf16(k0, qr[d0], s0, 0, 0, 0);
;         s1 = __builtin_amdgcn_mfma_f32_32x32x16_bf16(k1, qr[d0], s1, 0, 0, 0);
;     }
;     if (64 * t + 63 > qlo) {
; #pragma unroll
;         for (int r = 0; r < 16; ++r) { const int kv = 64 * t + crow(r, hi); if (kv > qpos) s0[r] = -INFINITY; if (kv + 32 > qpos) s1[r] = -INFINITY; }
;     }
;     float mx = fmaxf(s0[0], s1[0]);
; #pragma unroll
;     for (int r = 1; r < 16; ++r) mx = fmaxf(mx, fmaxf(s0[r], s1[r]));
;     mx = fmaxf(mx, __shfl_xor(mx, 32));
;     const float mnew = fmaxf(mrun, mx);
;     if (__any(mnew > mrun)) {
;         const float alpha = fexp2(mrun - mnew); lrun *= alpha;
; #pragma unroll
;         for (int r = 0; r < 16; ++r) { o0[r] *= alpha; o1[r] *= alpha; }
;     }
;     mrun = mnew;
.Lqkonly_O:
	s_waitcnt lgkmcnt(9)
	v_mfma_f32_32x32x16_bf16 v[206:221], v[124:127], v[78:81], v[206:221]
	ds_read_b128 v[148:151], v112 offset:17760
	ds_read_b128 v[152:155], v112 offset:22368
	s_waitcnt lgkmcnt(6)
	v_mfma_f32_32x32x16_bf16 v[222:237], v[128:131], v[78:81], v[222:237]
	s_waitcnt lgkmcnt(5)
	v_mfma_f32_32x32x16_bf16 v[206:221], v[132:135], v[74:77], v[206:221]
	s_waitcnt lgkmcnt(4)
	v_mfma_f32_32x32x16_bf16 v[222:237], v[136:139], v[74:77], v[222:237]
	s_waitcnt lgkmcnt(3)
	v_mfma_f32_32x32x16_bf16 v[206:221], v[140:143], v[70:73], v[206:221]
	s_waitcnt lgkmcnt(2)
	v_mfma_f32_32x32x16_bf16 v[222:237], v[144:147], v[70:73], v[222:237]
	s_waitcnt lgkmcnt(1)
	v_mfma_f32_32x32x16_bf16 v[206:221], v[148:151], v[66:69], v[206:221]
	s_waitcnt lgkmcnt(0)
	v_mfma_f32_32x32x16_bf16 v[222:237], v[152:155], v[66:69], v[222:237]
	s_nop 10
.Lmax_O:
	s_add_i32 s7, s6, 63
	s_cmp_gt_i32 s7, s21
	s_cbranch_scc0 .Lnomask_O
	v_add_u32_e32 v115, s6, v100
	v_add_u32_e32 v116, 0, v115
	v_cmp_le_i32_e32 vcc, v116, v110
	s_nop 1
	v_cndmask_b32_e32 v206, v205, v206, vcc
	v_add_u32_e32 v116, 1, v115
	v_cmp_le_i32_e32 vcc, v116, v110
	s_nop 1
	v_cndmask_b32_e32 v207, v205, v207, vcc
	v_add_u32_e32 v116, 2, v115
	v_cmp_le_i32_e32 vcc, v116, v110
	s_nop 1
	v_cndmask_b32_e32 v208, v205, v208, vcc
	v_add_u32_e32 v116, 3, v115
	v_cmp_le_i32_e32 vcc, v116, v110
	s_nop 1
	v_cndmask_b32_e32 v209, v205, v209, vcc
	v_add_u32_e32 v116, 8, v115
	v_cmp_le_i32_e32 vcc, v116, v110
	s_nop 1
	v_cndmask_b32_e32 v210, v205, v210, vcc
	v_add_u32_e32 v116, 9, v115
	v_cmp_le_i32_e32 vcc, v116, v110
	s_nop 1
	v_cndmask_b32_e32 v211, v205, v211, vcc
	v_add_u32_e32 v116, 10, v115
	v_cmp_le_i32_e32 vcc, v116, v110
	s_nop 1
	v_cndmask_b32_e32 v212, v205, v212, vcc
	v_add_u32_e32 v116, 11, v115
	v_cmp_le_i32_e32 vcc, v116, v110
	s_nop 1
	v_cndmask_b32_e32 v213, v205, v213, vcc
	v_add_u32_e32 v116, 16, v115
	v_cmp_le_i32_e32 vcc, v116, v110
	s_nop 1
	v_cndmask_b32_e32 v214, v205, v214, vcc
	v_add_u32_e32 v116, 17, v115
	v_cmp_le_i32_e32 vcc, v116, v110
	s_nop 1
	v_cndmask_b32_e32 v215, v205, v215, vcc
	v_add_u32_e32 v116, 18, v115
	v_cmp_le_i32_e32 vcc, v116, v110
	s_nop 1
	v_cndmask_b32_e32 v216, v205, v216, vcc
	v_add_u32_e32 v116, 19, v115
	v_cmp_le_i32_e32 vcc, v116, v110
	s_nop 1
	v_cndmask_b32_e32 v217, v205, v217, vcc
	v_add_u32_e32 v116, 24, v115
	v_cmp_le_i32_e32 vcc, v116, v110
	s_nop 1
	v_cndmask_b32_e32 v218, v205, v218, vcc
	v_add_u32_e32 v116, 25, v115
	v_cmp_le_i32_e32 vcc, v116, v110
	s_nop 1
	v_cndmask_b32_e32 v219, v205, v219, vcc
	v_add_u32_e32 v116, 26, v115
	v_cmp_le_i32_e32 vcc, v116, v110
	s_nop 1
	v_cndmask_b32_e32 v220, v205, v220, vcc
	v_add_u32_e32 v116, 27, v115
	v_cmp_le_i32_e32 vcc, v116, v110
	s_nop 1
	v_cndmask_b32_e32 v221, v205, v221, vcc
	v_add_u32_e32 v116, 32, v115
	v_cmp_le_i32_e32 vcc, v116, v110
	s_nop 1
	v_cndmask_b32_e32 v222, v205, v222, vcc
	v_add_u32_e32 v116, 33, v115
	v_cmp_le_i32_e32 vcc, v116, v110
	s_nop 1
	v_cndmask_b32_e32 v223, v205, v223, vcc
	v_add_u32_e32 v116, 34, v115
	v_cmp_le_i32_e32 vcc, v116, v110
	s_nop 1
	v_cndmask_b32_e32 v224, v205, v224, vcc
	v_add_u32_e32 v116, 35, v115
	v_cmp_le_i32_e32 vcc, v116, v110
	s_nop 1
	v_cndmask_b32_e32 v225, v205, v225, vcc
	v_add_u32_e32 v116, 40, v115
	v_cmp_le_i32_e32 vcc, v116, v110
	s_nop 1
	v_cndmask_b32_e32 v226, v205, v226, vcc
	v_add_u32_e32 v116, 41, v115
	v_cmp_le_i32_e32 vcc, v116, v110
	s_nop 1
	v_cndmask_b32_e32 v227, v205, v227, vcc
	v_add_u32_e32 v116, 42, v115
	v_cmp_le_i32_e32 vcc, v116, v110
	s_nop 1
	v_cndmask_b32_e32 v228, v205, v228, vcc
	v_add_u32_e32 v116, 43, v115
	v_cmp_le_i32_e32 vcc, v116, v110
	s_nop 1
	v_cndmask_b32_e32 v229, v205, v229, vcc
	v_add_u32_e32 v116, 48, v115
	v_cmp_le_i32_e32 vcc, v116, v110
	s_nop 1
	v_cndmask_b32_e32 v230, v205, v230, vcc
	v_add_u32_e32 v116, 49, v115
	v_cmp_le_i32_e32 vcc, v116, v110
	s_nop 1
	v_cndmask_b32_e32 v231, v205, v231, vcc
	v_add_u32_e32 v116, 50, v115
	v_cmp_le_i32_e32 vcc, v116, v110
	s_nop 1
	v_cndmask_b32_e32 v232, v205, v232, vcc
	v_add_u32_e32 v116, 51, v115
	v_cmp_le_i32_e32 vcc, v116, v110
	s_nop 1
	v_cndmask_b32_e32 v233, v205, v233, vcc
	v_add_u32_e32 v116, 56, v115
	v_cmp_le_i32_e32 vcc, v116, v110
	s_nop 1
	v_cndmask_b32_e32 v234, v205, v234, vcc
	v_add_u32_e32 v116, 57, v115
	v_cmp_le_i32_e32 vcc, v116, v110
	s_nop 1
	v_cndmask_b32_e32 v235, v205, v235, vcc
	v_add_u32_e32 v116, 58, v115
	v_cmp_le_i32_e32 vcc, v116, v110
	s_nop 1
	v_cndmask_b32_e32 v236, v205, v236, vcc
	v_add_u32_e32 v116, 59, v115
	v_cmp_le_i32_e32 vcc, v116, v110
	s_nop 1
	v_cndmask_b32_e32 v237, v205, v237, vcc
.Lnomask_O:
	v_max3_f32 v0, v206, v222, v207
	v_max3_f32 v115, v223, v208, v224
	v_max3_f32 v0, v0, v209, v225
	v_max3_f32 v115, v115, v210, v226
	v_max3_f32 v0, v0, v211, v227
	v_max3_f32 v115, v115, v212, v228
	v_max3_f32 v0, v0, v213, v229
	v_max3_f32 v115, v115, v214, v230
	v_max3_f32 v0, v0, v215, v231
	v_max3_f32 v115, v115, v216, v232
	v_max3_f32 v0, v0, v217, v233
	v_max3_f32 v115, v115, v218, v234
	v_max3_f32 v0, v0, v219, v235
	v_max3_f32 v115, v115, v220, v236
	v_max3_f32 v0, v0, v221, v237
	v_max_f32_e32 v0, v0, v115
	ds_bpermute_b32 v115, v107, v0
	s_waitcnt lgkmcnt(0)
	v_max3_f32 v0, v114, v0, v115
	v_add_f32_e32 v115, 0x41c00000, v114
	v_cmp_gt_f32_e32 vcc, v0, v115
	s_cbranch_vccz .Lnoresc_O
	v_sub_f32_e32 v114, v114, v0
	v_exp_f32_e32 v114, v114
	s_nop 0
	v_mul_f32_e32 v109, v109, v114
	v_pk_mul_f32 v[32:33], v[32:33], v[114:115] op_sel_hi:[1,0]
	v_pk_mul_f32 v[30:31], v[30:31], v[114:115] op_sel_hi:[1,0]
	v_pk_mul_f32 v[28:29], v[28:29], v[114:115] op_sel_hi:[1,0]
	v_pk_mul_f32 v[26:27], v[26:27], v[114:115] op_sel_hi:[1,0]
	v_pk_mul_f32 v[24:25], v[24:25], v[114:115] op_sel_hi:[1,0]
	v_pk_mul_f32 v[22:23], v[22:23], v[114:115] op_sel_hi:[1,0]
	v_pk_mul_f32 v[20:21], v[20:21], v[114:115] op_sel_hi:[1,0]
	v_pk_mul_f32 v[18:19], v[18:19], v[114:115] op_sel_hi:[1,0]
	v_pk_mul_f32 v[16:17], v[16:17], v[114:115] op_sel_hi:[1,0]
	v_pk_mul_f32 v[14:15], v[14:15], v[114:115] op_sel_hi:[1,0]
	v_pk_mul_f32 v[12:13], v[12:13], v[114:115] op_sel_hi:[1,0]
	v_pk_mul_f32 v[10:11], v[10:11], v[114:115] op_sel_hi:[1,0]
	v_pk_mul_f32 v[8:9], v[8:9], v[114:115] op_sel_hi:[1,0]
	v_pk_mul_f32 v[6:7], v[6:7], v[114:115] op_sel_hi:[1,0]
	v_pk_mul_f32 v[4:5], v[4:5], v[114:115] op_sel_hi:[1,0]
	v_pk_mul_f32 v[2:3], v[2:3], v[114:115] op_sel_hi:[1,0]
	v_mov_b32_e32 v114, v0
; #define LAS __attribute__((address_space(3)))
; __device__ __forceinline__ unsigned pk_bf16(float lo, float hi) { const f32x2_t v = {lo, hi}; const bf16x2_t b = __builtin_convertvector(v, bf16x2_t); return __builtin_bit_cast(unsigned, b); }
; __device__ __forceinline__ float fexp2(float x) { return __builtin_amdgcn_exp2f(x); }
; __device__ __forceinline__ void attn_tile(int t, int buf, LAS unsigned char* lds, const bf16x8 (&qr)[4], float cq2, int qlo, int qpos, int q32, int hi,
;                                           float& mrun, float& lrun, f32x16& o0, f32x16& o1) {
;     ...
;     f32x2 ls2 = (f32x2){0.f, 0.f};
; #pragma unroll
;     for (int r = 0; r < 16; r += 2) {
;         const f32x2 d0 = (f32x2){s0[r], s0[r + 1]} - mnew, d1 = (f32x2){s1[r], s1[r + 1]} - mnew;
;         f32x2 e0, e1; e0.x = fexp2(d0.x); e0.y = fexp2(d0.y); e1.x = fexp2(d1.x); e1.y = fexp2(d1.y);
;         s0[r] = e0.x; s0[r + 1] = e0.y; s1[r] = e1.x; s1[r + 1] = e1.y;
;         ls2 += e0 + e1;
;     }
;     lrun += ls2.x + ls2.y;
; #pragma unroll
;     for (int p = 0; p < 2; ++p)
; #pragma unroll
;         for (int sx = 0; sx < 2; ++sx) {
;             u32x4 pw;
;             if (p == 0) pw = (u32x4){pk_bf16(s0[8 * sx + 0], s0[8 * sx + 1]), pk_bf16(s0[8 * sx + 2], s0[8 * sx + 3]), pk_bf16(s0[8 * sx + 4], s0[8 * sx + 5]), pk_bf16(s0[8 * sx + 6], s0[8 * sx + 7])};
;             else        pw = (u32x4){pk_bf16(s1[8 * sx + 0], s1[8 * sx + 1]), pk_bf16(s1[8 * sx + 2], s1[8 * sx + 3]), pk_bf16(s1[8 * sx + 4], s1[8 * sx + 5]), pk_bf16(s1[8 * sx + 6], s1[8 * sx + 7])};
;             const bf16x8 pf = __builtin_bit_cast(bf16x8, pw);
;             const int ko = (32 * p + 16 * sx + 4 * hi) * 2;
;             const u32x2 a0 = *(const LAS u32x2*)(Vt + q32 * 136 + ko), a1 = *(const LAS u32x2*)(Vt + q32 * 136 + ko + 16);
;             const u32x2 b0 = *(const LAS u32x2*)(Vt + (32 + q32) * 136 + ko), b1 = *(const LAS u32x2*)(Vt + (32 + q32) * 136 + ko + 16);
;             const bf16x8 vf0 = __builtin_bit_cast(bf16x8, (u32x4){a0.x, a0.y, a1.x, a1.y});
;             const bf16x8 vf1 = __builtin_bit_cast(bf16x8, (u32x4){b0.x, b0.y, b1.x, b1.y});
;             o0 = __builtin_amdgcn_mfma_f32_32x32x16_bf16(vf0, pf, o0, 0, 0, 0);
;             o1 = __builtin_amdgcn_mfma_f32_32x32x16_bf16(vf1, pf, o1, 0, 0, 0);
;         }
.Lnoresc_O:
	s_mov_b32 s27, 1
	s_branch .Lend_O
.Lnoproc_O:
	s_mov_b32 s27, 0
	s_cmp_eq_u32 s26, 0
	s_cbranch_scc1 .Lend_O
	v_add_u32_e32 v122, 0x6800, v113
	v_add_u32_e32 v123, 0x7800, v113
	ds_read2_b64 v[166:169], v122 offset0:32 offset1:34
	ds_read2_b64 v[170:173], v123 offset0:64 offset1:66
	ds_read2_b64 v[174:177], v122 offset0:36 offset1:38
	ds_read2_b64 v[178:181], v123 offset0:68 offset1:70
	ds_read2_b64 v[182:185], v122 offset0:40 offset1:42
	ds_read2_b64 v[186:189], v123 offset0:72 offset1:74
	ds_read2_b64 v[190:193], v122 offset0:44 offset1:46
	ds_read2_b64 v[194:197], v123 offset0:76 offset1:78
	v_pk_add_f32 v[34:35], v[34:35], v[114:115] op_sel_hi:[1,0] neg_lo:[0,1] neg_hi:[0,1]
	v_pk_add_f32 v[36:37], v[36:37], v[114:115] op_sel_hi:[1,0] neg_lo:[0,1] neg_hi:[0,1]
	v_pk_add_f32 v[38:39], v[38:39], v[114:115] op_sel_hi:[1,0] neg_lo:[0,1] neg_hi:[0,1]
	v_pk_add_f32 v[40:41], v[40:41], v[114:115] op_sel_hi:[1,0] neg_lo:[0,1] neg_hi:[0,1]
	v_exp_f32_e32 v34, v34
	v_exp_f32_e32 v35, v35
	v_exp_f32_e32 v36, v36
	v_exp_f32_e32 v37, v37
	v_exp_f32_e32 v38, v38
	v_exp_f32_e32 v39, v39
	v_exp_f32_e32 v40, v40
	v_exp_f32_e32 v41, v41
	v_cvt_pk_bf16_f32 v118, v34, v35
	v_cvt_pk_bf16_f32 v119, v36, v37
	v_cvt_pk_bf16_f32 v120, v38, v39
	v_cvt_pk_bf16_f32 v121, v40, v41
	v_pk_add_f32 v[116:117], v[34:35], v[36:37]
	v_pk_add_f32 v[38:39], v[38:39], v[40:41]
	v_pk_add_f32 v[116:117], v[116:117], v[38:39]
	s_waitcnt lgkmcnt(0)
	v_mfma_f32_32x32x16_bf16 v[18:33], v[166:169], v[118:121], v[18:33]
	v_mfma_f32_32x32x16_bf16 v[2:17], v[170:173], v[118:121], v[2:17]
	v_pk_add_f32 v[42:43], v[42:43], v[114:115] op_sel_hi:[1,0] neg_lo:[0,1] neg_hi:[0,1]
	v_pk_add_f32 v[44:45], v[44:45], v[114:115] op_sel_hi:[1,0] neg_lo:[0,1] neg_hi:[0,1]
	v_pk_add_f32 v[46:47], v[46:47], v[114:115] op_sel_hi:[1,0] neg_lo:[0,1] neg_hi:[0,1]
	v_pk_add_f32 v[48:49], v[48:49], v[114:115] op_sel_hi:[1,0] neg_lo:[0,1] neg_hi:[0,1]
	v_exp_f32_e32 v42, v42
	v_exp_f32_e32 v43, v43
	v_exp_f32_e32 v44, v44
	v_exp_f32_e32 v45, v45
	v_exp_f32_e32 v46, v46
	v_exp_f32_e32 v47, v47
	v_exp_f32_e32 v48, v48
	v_exp_f32_e32 v49, v49
	v_cvt_pk_bf16_f32 v118, v42, v43
	v_cvt_pk_bf16_f32 v119, v44, v45
	v_cvt_pk_bf16_f32 v120, v46, v47
	v_cvt_pk_bf16_f32 v121, v48, v49
	v_pk_add_f32 v[42:43], v[42:43], v[44:45]
	v_pk_add_f32 v[46:47], v[46:47], v[48:49]
	v_pk_add_f32 v[42:43], v[42:43], v[46:47]
	v_pk_add_f32 v[116:117], v[116:117], v[42:43]
	v_mfma_f32_32x32x16_bf16 v[18:33], v[174:177], v[118:121], v[18:33]
	v_mfma_f32_32x32x16_bf16 v[2:17], v[178:181], v[118:121], v[2:17]
	v_pk_add_f32 v[50:51], v[50:51], v[114:115] op_sel_hi:[1,0] neg_lo:[0,1] neg_hi:[0,1]
	v_pk_add_f32 v[52:53], v[52:53], v[114:115] op_sel_hi:[1,0] neg_lo:[0,1] neg_hi:[0,1]
	v_pk_add_f32 v[54:55], v[54:55], v[114:115] op_sel_hi:[1,0] neg_lo:[0,1] neg_hi:[0,1]
	v_pk_add_f32 v[56:57], v[56:57], v[114:115] op_sel_hi:[1,0] neg_lo:[0,1] neg_hi:[0,1]
	v_exp_f32_e32 v50, v50
	v_exp_f32_e32 v51, v51
	v_exp_f32_e32 v52, v52
	v_exp_f32_e32 v53, v53
	v_exp_f32_e32 v54, v54
	v_exp_f32_e32 v55, v55
	v_exp_f32_e32 v56, v56
	v_exp_f32_e32 v57, v57
	v_cvt_pk_bf16_f32 v118, v50, v51
	v_cvt_pk_bf16_f32 v119, v52, v53
	v_cvt_pk_bf16_f32 v120, v54, v55
	v_cvt_pk_bf16_f32 v121, v56, v57
	v_pk_add_f32 v[50:51], v[50:51], v[52:53]
	v_pk_add_f32 v[54:55], v[54:55], v[56:57]
	v_pk_add_f32 v[50:51], v[50:51], v[54:55]
	v_pk_add_f32 v[116:117], v[116:117], v[50:51]
	v_mfma_f32_32x32x16_bf16 v[18:33], v[182:185], v[118:121], v[18:33]
	v_mfma_f32_32x32x16_bf16 v[2:17], v[186:189], v[118:121], v[2:17]
	v_pk_add_f32 v[58:59], v[58:59], v[114:115] op_sel_hi:[1,0] neg_lo:[0,1] neg_hi:[0,1]
	v_pk_add_f32 v[60:61], v[60:61], v[114:115] op_sel_hi:[1,0] neg_lo:[0,1] neg_hi:[0,1]
	v_pk_add_f32 v[62:63], v[62:63], v[114:115] op_sel_hi:[1,0] neg_lo:[0,1] neg_hi:[0,1]
	v_pk_add_f32 v[64:65], v[64:65], v[114:115] op_sel_hi:[1,0] neg_lo:[0,1] neg_hi:[0,1]
	v_exp_f32_e32 v58, v58
	v_exp_f32_e32 v59, v59
	v_exp_f32_e32 v60, v60
	v_exp_f32_e32 v61, v61
	v_exp_f32_e32 v62, v62
	v_exp_f32_e32 v63, v63
	v_exp_f32_e32 v64, v64
	v_exp_f32_e32 v65, v65
	v_cvt_pk_bf16_f32 v118, v58, v59
	v_cvt_pk_bf16_f32 v119, v60, v61
	v_cvt_pk_bf16_f32 v120, v62, v63
	v_cvt_pk_bf16_f32 v121, v64, v65
	v_pk_add_f32 v[58:59], v[58:59], v[60:61]
	v_pk_add_f32 v[62:63], v[62:63], v[64:65]
	v_pk_add_f32 v[58:59], v[58:59], v[62:63]
	v_pk_add_f32 v[116:117], v[116:117], v[58:59]
	v_mfma_f32_32x32x16_bf16 v[18:33], v[190:193], v[118:121], v[18:33]
	v_mfma_f32_32x32x16_bf16 v[2:17], v[194:197], v[118:121], v[2:17]
	v_add_f32_e32 v116, v116, v117
	v_add_f32_e32 v109, v109, v116
; __device__ __forceinline__ void attn_tile(int t, int buf, LAS unsigned char* lds, const bf16x8 (&qr)[4], float cq2, int qlo, int qpos, int q32, int hi,
;                                           float& mrun, float& lrun, f32x16& o0, f32x16& o1) {
;     ...
;     f32x2 ls2 = (f32x2){0.f, 0.f};
; #pragma unroll
;     for (int r = 0; r < 16; r += 2) {
;         const f32x2 d0 = (f32x2){s0[r], s0[r + 1]} - mnew, d1 = (f32x2){s1[r], s1[r + 1]} - mnew;
;         f32x2 e0, e1; e0.x = fexp2(d0.x); e0.y = fexp2(d0.y); e1.x = fexp2(d1.x); e1.y = fexp2(d1.y);
;         s0[r] = e0.x; s0[r + 1] = e0.y; s1[r] = e1.x; s1[r + 1] = e1.y;
;         ls2 += e0 + e1;
;     }
;     lrun += ls2.x + ls2.y;
; #pragma unroll
;     for (int p = 0; p < 2; ++p)
; #pragma unroll
;         for (int sx = 0; sx < 2; ++sx) {
;             u32x4 pw;
;             if (p == 0) pw = (u32x4){pk_bf16(s0[8 * sx + 0], s0[8 * sx + 1]), pk_bf16(s0[8 * sx + 2], s0[8 * sx + 3]), pk_bf16(s0[8 * sx + 4], s0[8 * sx + 5]), pk_bf16(s0[8 * sx + 6], s0[8 * sx + 7])};
;             else        pw = (u32x4){pk_bf16(s1[8 * sx + 0], s1[8 * sx + 1]), pk_bf16(s1[8 * sx + 2], s1[8 * sx + 3]), pk_bf16(s1[8 * sx + 4], s1[8 * sx + 5]), pk_bf16(s1[8 * sx + 6], s1[8 * sx + 7])};
;             const bf16x8 pf = __builtin_bit_cast(bf16x8, pw);
;             const int ko = (32 * p + 16 * sx + 4 * hi) * 2;
;             const u32x2 a0 = *(const LAS u32x2*)(Vt + q32 * 136 + ko), a1 = *(const LAS u32x2*)(Vt + q32 * 136 + ko + 16);
;             const u32x2 b0 = *(const LAS u32x2*)(Vt + (32 + q32) * 136 + ko), b1 = *(const LAS u32x2*)(Vt + (32 + q32) * 136 + ko + 16);
;             const bf16x8 vf0 = __builtin_bit_cast(bf16x8, (u32x4){a0.x, a0.y, a1.x, a1.y});
; __device__ __forceinline__ void attn_unit(const AttnJob& J, LAS unsigned char* lds) {
;     ...
;     for (int t = 0; t < J.NT; t += 2) {
;         attn_stage(lds, 0, kA, vA);
;         __syncthreads();
;         if (t + 2 < J.NT) attn_load(J, t + 2, kA, vA);
;         if (active && 64 * t <= qlo + 31) attn_tile(t, 0, lds, qr, cq2, qlo, qpos, q32, hi, mrun, lrun, o0, o1);
;         if (t + 1 < J.NT) {
;             attn_stage(lds, 1, kB, vB);
;             __syncthreads();
;             if (t + 3 < J.NT) attn_load(J, t + 3, kB, vB);
;             if (active && 64 * (t + 1) <= qlo + 31) attn_tile(t + 1, 1, lds, qr, cq2, qlo, qpos, q32, hi, mrun, lrun, o0, o1);
;         }
;     }
.Lend_O:
	s_add_i32 s22, s22, 2
	v_add_u32_e32 v111, 0x200, v111
	s_cmp_lt_u32 s22, s20
	s_cbranch_scc1 .Lslot_E
	s_waitcnt vmcnt(0)
	ds_write_b16 v157, v94 offset:35584
	ds_write_b16_d16_hi v157, v94 offset:35720
	ds_write_b16 v157, v95 offset:35856
	ds_write_b16_d16_hi v157, v95 offset:35992
	ds_write_b16 v157, v96 offset:36128
	ds_write_b16_d16_hi v157, v96 offset:36264
	ds_write_b16 v157, v97 offset:36400
	ds_write_b16_d16_hi v157, v97 offset:36536
	s_waitcnt lgkmcnt(0)
	s_barrier
	s_cmp_eq_u32 s27, 0
	s_cbranch_scc1 .LBB0_663
	v_add_u32_e32 v122, 0x8800, v113
	v_add_u32_e32 v123, 0x9800, v113
	ds_read2_b64 v[166:169], v122 offset0:96 offset1:98
	ds_read2_b64 v[170:173], v123 offset0:128 offset1:130
	ds_read2_b64 v[174:177], v122 offset0:100 offset1:102
	ds_read2_b64 v[178:181], v123 offset0:132 offset1:134
	ds_read2_b64 v[182:185], v122 offset0:104 offset1:106
	ds_read2_b64 v[186:189], v123 offset0:136 offset1:138
	ds_read2_b64 v[190:193], v122 offset0:108 offset1:110
	ds_read2_b64 v[194:197], v123 offset0:140 offset1:142
	v_pk_add_f32 v[206:207], v[206:207], v[114:115] op_sel_hi:[1,0] neg_lo:[0,1] neg_hi:[0,1]
	v_pk_add_f32 v[208:209], v[208:209], v[114:115] op_sel_hi:[1,0] neg_lo:[0,1] neg_hi:[0,1]
	v_pk_add_f32 v[210:211], v[210:211], v[114:115] op_sel_hi:[1,0] neg_lo:[0,1] neg_hi:[0,1]
	v_pk_add_f32 v[212:213], v[212:213], v[114:115] op_sel_hi:[1,0] neg_lo:[0,1] neg_hi:[0,1]
	v_exp_f32_e32 v206, v206
	v_exp_f32_e32 v207, v207
	v_exp_f32_e32 v208, v208
	v_exp_f32_e32 v209, v209
	v_exp_f32_e32 v210, v210
	v_exp_f32_e32 v211, v211
	v_exp_f32_e32 v212, v212
	v_exp_f32_e32 v213, v213
	v_cvt_pk_bf16_f32 v118, v206, v207
	v_cvt_pk_bf16_f32 v119, v208, v209
	v_cvt_pk_bf16_f32 v120, v210, v211
	v_cvt_pk_bf16_f32 v121, v212, v213
	v_pk_add_f32 v[116:117], v[206:207], v[208:209]
	v_pk_add_f32 v[210:211], v[210:211], v[212:213]
	v_pk_add_f32 v[116:117], v[116:117], v[210:211]
	s_waitcnt lgkmcnt(0)
	v_mfma_f32_32x32x16_bf16 v[18:33], v[166:169], v[118:121], v[18:33]
	v_mfma_f32_32x32x16_bf16 v[2:17], v[170:173], v[118:121], v[2:17]
	v_pk_add_f32 v[214:215], v[214:215], v[114:115] op_sel_hi:[1,0] neg_lo:[0,1] neg_hi:[0,1]
	v_pk_add_f32 v[216:217], v[216:217], v[114:115] op_sel_hi:[1,0] neg_lo:[0,1] neg_hi:[0,1]
	v_pk_add_f32 v[218:219], v[218:219], v[114:115] op_sel_hi:[1,0] neg_lo:[0,1] neg_hi:[0,1]
	v_pk_add_f32 v[220:221], v[220:221], v[114:115] op_sel_hi:[1,0] neg_lo:[0,1] neg_hi:[0,1]
	v_exp_f32_e32 v214, v214
	v_exp_f32_e32 v215, v215
	v_exp_f32_e32 v216, v216
	v_exp_f32_e32 v217, v217
	v_exp_f32_e32 v218, v218
	v_exp_f32_e32 v219, v219
	v_exp_f32_e32 v220, v220
	v_exp_f32_e32 v221, v221
	v_cvt_pk_bf16_f32 v118, v214, v215
	v_cvt_pk_bf16_f32 v119, v216, v217
	v_cvt_pk_bf16_f32 v120, v218, v219
	v_cvt_pk_bf16_f32 v121, v220, v221
	v_pk_add_f32 v[214:215], v[214:215], v[216:217]
	v_pk_add_f32 v[218:219], v[218:219], v[220:221]
	v_pk_add_f32 v[214:215], v[214:215], v[218:219]
	v_pk_add_f32 v[116:117], v[116:117], v[214:215]
	v_mfma_f32_32x32x16_bf16 v[18:33], v[174:177], v[118:121], v[18:33]
	v_mfma_f32_32x32x16_bf16 v[2:17], v[178:181], v[118:121], v[2:17]
	v_pk_add_f32 v[222:223], v[222:223], v[114:115] op_sel_hi:[1,0] neg_lo:[0,1] neg_hi:[0,1]
	v_pk_add_f32 v[224:225], v[224:225], v[114:115] op_sel_hi:[1,0] neg_lo:[0,1] neg_hi:[0,1]
	v_pk_add_f32 v[226:227], v[226:227], v[114:115] op_sel_hi:[1,0] neg_lo:[0,1] neg_hi:[0,1]
	v_pk_add_f32 v[228:229], v[228:229], v[114:115] op_sel_hi:[1,0] neg_lo:[0,1] neg_hi:[0,1]
	v_exp_f32_e32 v222, v222
	v_exp_f32_e32 v223, v223
	v_exp_f32_e32 v224, v224
	v_exp_f32_e32 v225, v225
	v_exp_f32_e32 v226, v226
	v_exp_f32_e32 v227, v227
	v_exp_f32_e32 v228, v228
	v_exp_f32_e32 v229, v229
	v_cvt_pk_bf16_f32 v118, v222, v223
	v_cvt_pk_bf16_f32 v119, v224, v225
	v_cvt_pk_bf16_f32 v120, v226, v227
	v_cvt_pk_bf16_f32 v121, v228, v229
	v_pk_add_f32 v[222:223], v[222:223], v[224:225]
	v_pk_add_f32 v[226:227], v[226:227], v[228:229]
	v_pk_add_f32 v[222:223], v[222:223], v[226:227]
	v_pk_add_f32 v[116:117], v[116:117], v[222:223]
	v_mfma_f32_32x32x16_bf16 v[18:33], v[182:185], v[118:121], v[18:33]
	v_mfma_f32_32x32x16_bf16 v[2:17], v[186:189], v[118:121], v[2:17]
	v_pk_add_f32 v[230:231], v[230:231], v[114:115] op_sel_hi:[1,0] neg_lo:[0,1] neg_hi:[0,1]
	v_pk_add_f32 v[232:233], v[232:233], v[114:115] op_sel_hi:[1,0] neg_lo:[0,1] neg_hi:[0,1]
	v_pk_add_f32 v[234:235], v[234:235], v[114:115] op_sel_hi:[1,0] neg_lo:[0,1] neg_hi:[0,1]
	v_pk_add_f32 v[236:237], v[236:237], v[114:115] op_sel_hi:[1,0] neg_lo:[0,1] neg_hi:[0,1]
	v_exp_f32_e32 v230, v230
	v_exp_f32_e32 v231, v231
	v_exp_f32_e32 v232, v232
	v_exp_f32_e32 v233, v233
	v_exp_f32_e32 v234, v234
	v_exp_f32_e32 v235, v235
	v_exp_f32_e32 v236, v236
	v_exp_f32_e32 v237, v237
	v_cvt_pk_bf16_f32 v118, v230, v231
	v_cvt_pk_bf16_f32 v119, v232, v233
	v_cvt_pk_bf16_f32 v120, v234, v235
	v_cvt_pk_bf16_f32 v121, v236, v237
	v_pk_add_f32 v[230:231], v[230:231], v[232:233]
	v_pk_add_f32 v[234:235], v[234:235], v[236:237]
	v_pk_add_f32 v[230:231], v[230:231], v[234:235]
	v_pk_add_f32 v[116:117], v[116:117], v[230:231]
	v_mfma_f32_32x32x16_bf16 v[18:33], v[190:193], v[118:121], v[18:33]
	v_mfma_f32_32x32x16_bf16 v[2:17], v[194:197], v[118:121], v[2:17]
	v_add_f32_e32 v116, v116, v117
	v_add_f32_e32 v109, v109, v116
